# grid barrier: XCD leaders poll the monotonic top-level arrival counter directly (drops the separate release-generation hop), on top of early L1 invalidate
# speedup vs baseline: 1.0108x; 1.0108x over previous
.LBB0_602:
	s_or_b64 exec, exec, s[12:13]
	s_waitcnt vmcnt(0)
	v_readfirstlane_b32 s1, v2
	v_cvt_f32_u32_e32 v2, v0
	v_sub_u32_e32 v3, 0, v0
	v_add_u32_e32 v1, s1, v1
	v_readlane_b32 s2, v252, 53
	v_rcp_iflag_f32_e32 v2, v2
	v_readlane_b32 s3, v252, 54
	s_mov_b64 s[12:13], 0
	v_mul_f32_e32 v2, 0x4f7ffffe, v2
	v_cvt_u32_f32_e32 v2, v2
	v_mul_lo_u32 v3, v3, v2
	v_mul_hi_u32 v3, v2, v3
	v_add_u32_e32 v2, v2, v3
	v_mul_hi_u32 v2, v1, v2
	v_mul_lo_u32 v3, v2, v0
	v_sub_u32_e32 v3, v1, v3
	v_cmp_ge_u32_e32 vcc, v3, v0
	v_add_u32_e32 v4, 1, v2
	v_add_u32_e32 v1, 1, v1
	v_cndmask_b32_e32 v2, v2, v4, vcc
	v_sub_u32_e32 v4, v3, v0
	v_cndmask_b32_e32 v3, v3, v4, vcc
	v_cmp_ge_u32_e32 vcc, v3, v0
	v_add_u32_e32 v3, 1, v2
	s_nop 0
	v_cndmask_b32_e32 v2, v2, v3, vcc
	v_mul_lo_u32 v3, v0, v2
	v_add_u32_e32 v0, v3, v0
	v_mov_b32_e32 v4, v0
	v_cmp_ne_u32_e32 vcc, v1, v0
	v_mov_b64_e32 v[0:1], s[2:3]
	s_and_saveexec_b64 s[8:9], vcc
	s_cbranch_execz .LBB0_614
	v_readlane_b32 s2, v252, 51
	v_readlane_b32 s3, v252, 52
	s_mov_b64 s[18:19], 0
	s_nop 3
	global_load_dword v0, v197, s[2:3] sc1
	s_waitcnt vmcnt(0)
	v_cmp_lt_u32_e32 vcc, v0, v4
	s_and_saveexec_b64 s[12:13], vcc
	s_cbranch_execz .LBB0_613
	s_mov_b32 s1, 1
	s_branch .LBB0_606

.LBB0_608:
	v_readlane_b32 s2, v252, 51
	v_readlane_b32 s3, v252, 52
	s_add_i32 s1, s1, 1
	s_mov_b64 s[24:25], -1
	s_nop 2
	global_load_dword v0, v197, s[2:3] sc1
	s_waitcnt vmcnt(0)
	v_cmp_ge_u32_e32 vcc, v0, v4
	s_orn2_b64 s[22:23], vcc, exec
	s_branch .LBB0_605

.LBB0_656:
	s_or_b64 exec, exec, s[12:13]
	s_waitcnt vmcnt(0)
	v_readfirstlane_b32 s1, v2
	v_cvt_f32_u32_e32 v2, v0
	v_sub_u32_e32 v3, 0, v0
	v_add_u32_e32 v1, s1, v1
	v_readlane_b32 s2, v252, 53
	v_rcp_iflag_f32_e32 v2, v2
	v_readlane_b32 s3, v252, 54
	s_mov_b64 s[12:13], 0
	v_mul_f32_e32 v2, 0x4f7ffffe, v2
	v_cvt_u32_f32_e32 v2, v2
	v_mul_lo_u32 v3, v3, v2
	v_mul_hi_u32 v3, v2, v3
	v_add_u32_e32 v2, v2, v3
	v_mul_hi_u32 v2, v1, v2
	v_mul_lo_u32 v3, v2, v0
	v_sub_u32_e32 v3, v1, v3
	v_cmp_ge_u32_e32 vcc, v3, v0
	v_add_u32_e32 v4, 1, v2
	v_add_u32_e32 v1, 1, v1
	v_cndmask_b32_e32 v2, v2, v4, vcc
	v_sub_u32_e32 v4, v3, v0
	v_cndmask_b32_e32 v3, v3, v4, vcc
	v_cmp_ge_u32_e32 vcc, v3, v0
	v_add_u32_e32 v3, 1, v2
	s_nop 0
	v_cndmask_b32_e32 v2, v2, v3, vcc
	v_mul_lo_u32 v3, v0, v2
	v_add_u32_e32 v0, v3, v0
	v_mov_b32_e32 v4, v0
	v_cmp_ne_u32_e32 vcc, v1, v0
	v_mov_b64_e32 v[0:1], s[2:3]
	s_and_saveexec_b64 s[8:9], vcc
	s_cbranch_execz .LBB0_668
	v_readlane_b32 s2, v252, 51
	v_readlane_b32 s3, v252, 52
	s_mov_b64 s[18:19], 0
	s_nop 3
	global_load_dword v0, v197, s[2:3] sc1
	s_waitcnt vmcnt(0)
	v_cmp_lt_u32_e32 vcc, v0, v4
	s_and_saveexec_b64 s[12:13], vcc
	s_cbranch_execz .LBB0_667
	s_mov_b32 s26, s30
	s_mov_b32 s1, 1
	s_branch .LBB0_660

.LBB0_912:
	s_or_b64 exec, exec, s[12:13]
	s_waitcnt vmcnt(0)
	v_readfirstlane_b32 s2, v2
	v_cvt_f32_u32_e32 v2, v0
	v_sub_u32_e32 v3, 0, v0
	v_add_u32_e32 v1, s2, v1
	v_readlane_b32 s2, v252, 53
	v_rcp_iflag_f32_e32 v2, v2
	v_readlane_b32 s3, v252, 54
	s_mov_b64 s[12:13], 0
	v_mul_f32_e32 v2, 0x4f7ffffe, v2
	v_cvt_u32_f32_e32 v2, v2
	v_mul_lo_u32 v3, v3, v2
	v_mul_hi_u32 v3, v2, v3
	v_add_u32_e32 v2, v2, v3
	v_mul_hi_u32 v2, v1, v2
	v_mul_lo_u32 v3, v2, v0
	v_sub_u32_e32 v3, v1, v3
	v_cmp_ge_u32_e32 vcc, v3, v0
	v_add_u32_e32 v4, 1, v2
	v_add_u32_e32 v1, 1, v1
	v_cndmask_b32_e32 v2, v2, v4, vcc
	v_sub_u32_e32 v4, v3, v0
	v_cndmask_b32_e32 v3, v3, v4, vcc
	v_cmp_ge_u32_e32 vcc, v3, v0
	v_add_u32_e32 v3, 1, v2
	s_nop 0
	v_cndmask_b32_e32 v2, v2, v3, vcc
	v_mul_lo_u32 v3, v0, v2
	v_add_u32_e32 v0, v3, v0
	v_mov_b32_e32 v4, v0
	v_cmp_ne_u32_e32 vcc, v1, v0
	v_mov_b64_e32 v[0:1], s[2:3]
	s_and_saveexec_b64 s[8:9], vcc
	s_cbranch_execz .LBB0_924
	v_readlane_b32 s2, v252, 51
	v_readlane_b32 s3, v252, 52
	s_mov_b64 s[18:19], 0
	s_nop 3
	global_load_dword v0, v197, s[2:3] sc1
	s_waitcnt vmcnt(0)
	v_cmp_lt_u32_e32 vcc, v0, v4
	s_and_saveexec_b64 s[12:13], vcc
	s_cbranch_execz .LBB0_923
	s_mov_b32 s26, s30
	s_mov_b32 s2, 1
	s_branch .LBB0_916

.LBB0_918:
	v_readlane_b32 s14, v252, 51
	v_readlane_b32 s15, v252, 52
	s_add_i32 s2, s2, 1
	s_mov_b64 s[24:25], -1
	s_nop 2
	global_load_dword v0, v197, s[14:15] sc1
	s_waitcnt vmcnt(0)
	v_cmp_ge_u32_e32 vcc, v0, v4
	s_orn2_b64 s[22:23], vcc, exec
	s_branch .LBB0_915
